# table fill batched and done once per unit pair (k==0)
# baseline (speedup 1.0000x reference)
.LBB0_631:
	s_or_b64 exec, exec, s[4:5]
	s_cmp_eq_u64 s[2:3], 0
	s_cbranch_scc1 .Lnsa2_skipfill
	v_add_u32_e32 v206, 0, v200
	v_min_u32_e32 v206, 1407, v206
	v_cmp_lt_u32_e32 vcc, 703, v206
	v_mov_b32_e32 v213, 0
	s_nop 0
	v_cndmask_b32_e64 v207, 0, 1, vcc
	v_mul_u32_u24_e32 v208, 704, v207
	v_sub_u32_e32 v208, v206, v208
	v_subrev_u32_e32 v209, 96, v208
	v_max_i32_e32 v210, 0, v209
	v_min_i32_e32 v210, 0x80, v210
	v_lshlrev_b32_e32 v210, 2, v210
	v_add_u32_e32 v210, 0x20004, v210
	ds_read_b32 v210, v210
	v_mul_u32_u24_e32 v211, 0xb00, v207
	v_lshl_add_u32 v211, v208, 2, v211
	v_add_u32_e32 v211, 0x1d000, v211
	v_add_u32_e32 v218, 512, v200
	v_min_u32_e32 v218, 1407, v218
	v_cmp_lt_u32_e32 vcc, 703, v218
	v_mov_b32_e32 v225, 0
	s_nop 0
	v_cndmask_b32_e64 v219, 0, 1, vcc
	v_mul_u32_u24_e32 v220, 704, v219
	v_sub_u32_e32 v220, v218, v220
	v_subrev_u32_e32 v221, 96, v220
	v_max_i32_e32 v222, 0, v221
	v_min_i32_e32 v222, 0x80, v222
	v_lshlrev_b32_e32 v222, 2, v222
	v_add_u32_e32 v222, 0x20004, v222
	ds_read_b32 v222, v222
	v_mul_u32_u24_e32 v223, 0xb00, v219
	v_lshl_add_u32 v223, v220, 2, v223
	v_add_u32_e32 v223, 0x1d000, v223
	v_add_u32_e32 v230, 1024, v200
	v_min_u32_e32 v230, 1407, v230
	v_cmp_lt_u32_e32 vcc, 703, v230
	v_mov_b32_e32 v237, 0
	s_nop 0
	v_cndmask_b32_e64 v231, 0, 1, vcc
	v_mul_u32_u24_e32 v232, 704, v231
	v_sub_u32_e32 v232, v230, v232
	v_subrev_u32_e32 v233, 96, v232
	v_max_i32_e32 v234, 0, v233
	v_min_i32_e32 v234, 0x80, v234
	v_lshlrev_b32_e32 v234, 2, v234
	v_add_u32_e32 v234, 0x20004, v234
	ds_read_b32 v234, v234
	v_mul_u32_u24_e32 v235, 0xb00, v231
	v_lshl_add_u32 v235, v232, 2, v235
	v_add_u32_e32 v235, 0x1d000, v235
	s_waitcnt lgkmcnt(0)
	v_mul_lo_u32 v210, v210, 12
	v_add3_u32 v212, v210, v207, s81
	v_ashrrev_i32_e32 v213, 31, v212
	v_lshl_add_u64 v[212:213], v[212:213], 2, s[56:57]
	global_load_dword v214, v[212:213], off
	v_mul_lo_u32 v222, v222, 12
	v_add3_u32 v224, v222, v219, s81
	v_ashrrev_i32_e32 v225, 31, v224
	v_lshl_add_u64 v[224:225], v[224:225], 2, s[56:57]
	global_load_dword v226, v[224:225], off
	v_mul_lo_u32 v234, v234, 12
	v_add3_u32 v236, v234, v231, s81
	v_ashrrev_i32_e32 v237, 31, v236
	v_lshl_add_u64 v[236:237], v[236:237], 2, s[56:57]
	global_load_dword v238, v[236:237], off
	v_mov_b32_e32 v205, 0xf149f2ca
	v_mov_b32_e32 v204, 0x1ff
	s_waitcnt vmcnt(0)
	v_cmp_gt_u32_e32 vcc, v209, v204
	v_mul_f32_e32 v214, 0x41000000, v214
	s_nop 0
	v_cndmask_b32_e32 v214, v214, v205, vcc
	ds_write_b32 v211, v214
	v_cmp_gt_u32_e32 vcc, v221, v204
	v_mul_f32_e32 v226, 0x41000000, v226
	s_nop 0
	v_cndmask_b32_e32 v226, v226, v205, vcc
	ds_write_b32 v223, v226
	v_cmp_gt_u32_e32 vcc, v233, v204
	v_mul_f32_e32 v238, 0x41000000, v238
	s_nop 0
	v_cndmask_b32_e32 v238, v238, v205, vcc
	ds_write_b32 v235, v238
.Lnsa2_skipfill:
	v_readfirstlane_b32 s92, v200
	s_lshr_b32 s92, s92, 8
	s_and_b32 s92, s92, 1
	s_mul_i32 s93, s92, 0xb00
	s_add_i32 s93, s93, 0x1d000
	s_add_i32 s92, s93, 148
	s_add_i32 s94, s93, 276
	s_add_i32 s95, s93, 192
	s_add_i32 s96, s93, 320
	s_xor_b64 s[50:51], s[2:3], -1
	s_and_b64 s[0:1], s[2:3], exec
	s_cselect_b32 s61, s82, s80
	s_lshl_b32 s60, s61, 8
	v_and_b32_e32 v181, 0xc0, v2
	v_and_b32_e32 v151, 31, v2
	v_or_b32_e32 v182, s60, v181
	v_ashrrev_i32_e32 v3, 8, v2
	v_or_b32_e32 v0, v182, v151
	v_add_u32_e32 v185, s81, v3
	v_lshl_add_u64 v[146:147], s[34:35], 0, v[0:1]
	v_mad_u64_u32 v[4:5], s[0:1], v146, s73, v[138:139]
	v_lshlrev_b32_e32 v152, 6, v185
	v_bfe_u32 v186, v2, 5, 1
	v_mad_i32_i24 v5, v147, s73, v5
	v_ashrrev_i32_e32 v153, 31, v152
	v_ashrrev_i32_e32 v183, 3, v2
	v_lshl_add_u64 v[4:5], v[152:153], 1, v[4:5]
	v_lshlrev_b32_e32 v0, 4, v186
	v_med3_i32 v36, v183, 0, v141
	v_lshlrev_b32_e32 v38, 3, v2
	v_lshl_add_u64 v[24:25], v[4:5], 0, v[0:1]
	v_mul_u32_u24_e32 v36, 0x600, v36
	v_mov_b32_e32 v37, v1
	v_and_b32_e32 v150, 56, v38
	v_add_co_u32_e32 v28, vcc, s74, v24
	v_lshl_add_u64 v[36:37], v[36:37], 1, s[44:45]
	v_lshlrev_b32_e32 v44, 1, v150
	v_mov_b32_e32 v45, v1
	v_lshl_add_u64 v[32:33], v[24:25], 0, s[20:21]
	v_addc_co_u32_e32 v29, vcc, 0, v25, vcc
	v_lshl_add_u64 v[40:41], v[36:37], 0, v[44:45]
	global_load_dwordx4 v[4:7], v[24:25], off
	global_load_dwordx4 v[8:11], v[24:25], off offset:32
	global_load_dwordx4 v[12:15], v[32:33], off offset:32
	global_load_dwordx4 v[16:19], v[32:33], off offset:64
	global_load_dwordx4 v[20:23], v[24:25], off offset:64
	s_nop 0
	global_load_dwordx4 v[24:27], v[24:25], off offset:96
	s_nop 0
	global_load_dwordx4 v[28:31], v[28:29], off
	s_nop 0
	global_load_dwordx4 v[32:35], v[32:33], off offset:96
	s_nop 0
	global_load_dwordx4 v[36:39], v[40:41], off offset:1792
	s_nop 0
	global_load_dwordx4 v[40:43], v[40:41], off offset:1920
	v_or_b32_e32 v148, 32, v146
	v_mov_b32_e32 v149, v147
	v_lshl_add_u64 v[46:47], v[146:147], 2, s[18:19]
	v_lshl_add_u64 v[48:49], v[148:149], 2, s[18:19]
	global_load_dword v187, v[46:47], off
	global_load_dword v188, v[48:49], off
	v_lshlrev_b32_e32 v47, 7, v2
	v_and_b32_e32 v46, 63, v2
	v_lshlrev_b32_e32 v48, 4, v2
	v_mad_i32_i24 v175, v3, s72, 0
	v_and_b32_e32 v3, 0xffffe000, v47
	v_lshlrev_b32_e32 v46, 4, v46
	v_mul_lo_u32 v47, v183, s75
	v_and_b32_e32 v48, 0x70, v48
	v_add_u32_e32 v3, 0, v3
	v_and_b32_e32 v49, 16, v2
	v_lshrrev_b32_e32 v50, 2, v2
	v_mul_u32_u24_e32 v51, 0x90, v151
	v_add3_u32 v140, 0, v47, v48
	v_add_u32_e32 v176, v3, v46
	v_lshlrev_b32_e32 v184, 2, v186
	v_lshlrev_b32_e32 v3, 2, v2
	v_mad_u64_u32 v[142:143], s[0:1], v183, 48, v[140:141]
	v_add3_u32 v178, 0, v51, v0
	v_and_or_b32 v0, v50, 3, v184
	v_and_or_b32 v3, v3, 12, v49
	v_mul_u32_u24_e32 v0, 0xc0, v0
	v_lshlrev_b32_e32 v3, 1, v3
	v_add3_u32 v179, 0, v0, v3
	v_bitop3_b32 v0, v2, 31, v170 bitop3:0xe0
	s_lshl_b32 s84, s61, 2
	v_lshl_add_u64 v[144:145], s[44:45], 0, v[44:45]
	v_mad_u64_u32 v[154:155], s[0:1], v146, s73, 0
	v_sub_u32_e32 v192, v0, v184
	v_mov_b32_e32 v0, v1
	v_mov_b32_e32 v2, v1
	v_mov_b32_e32 v3, v1
	s_mov_b32 s85, 0
	s_add_i32 s83, s84, 4
	v_or_b32_e32 v143, 31, v182
	v_or_b32_e32 v177, 63, v182
	v_mad_i32_i24 v155, v147, s73, v155
	v_add_u32_e32 v190, 0xffffff41, v182
	v_add_u32_e32 v191, 0xffffff61, v182
	v_add_u32_e32 v180, 64, v183
	s_add_i32 s86, s60, 0x100
	v_mov_b32_e32 v193, 0xf149f2ca
	v_mov_b32_e32 v194, 0xf149f2ca
	s_mov_b32 s87, 0
	s_mov_b32 s0, 0
	v_mov_b64_e32 v[156:157], v[0:1]
	s_waitcnt vmcnt(11)
	ds_write_b128 v176, v[4:7] offset:53248
	s_waitcnt vmcnt(10)
	ds_write_b128 v176, v[8:11] offset:54272
	s_waitcnt vmcnt(7)
	ds_write_b128 v176, v[20:23] offset:55296
	s_waitcnt vmcnt(6)
	ds_write_b128 v176, v[24:27] offset:56320
	s_waitcnt vmcnt(5)
	ds_write_b128 v176, v[28:31] offset:57344
	ds_write_b128 v176, v[12:15] offset:58368
	ds_write_b128 v176, v[16:19] offset:59392
	s_waitcnt vmcnt(4)
	ds_write_b128 v176, v[32:35] offset:60416
	s_waitcnt lgkmcnt(0)
	s_barrier
	s_waitcnt vmcnt(3)
	ds_write_b128 v140, v[36:39]
	s_waitcnt vmcnt(2)
	ds_write_b128 v142, v[40:43] offset:18432
	s_waitcnt lgkmcnt(0)
	s_barrier
	ds_read_b32 v189, v175 offset:43524
	v_mov_b32_e32 v16, v1
	v_mov_b32_e32 v17, v1
	v_mov_b32_e32 v4, v1
	v_mov_b32_e32 v5, v1
	v_mov_b32_e32 v6, v1
	v_mov_b32_e32 v7, v1
	v_mov_b32_e32 v8, v1
	v_mov_b32_e32 v9, v1
	v_mov_b32_e32 v10, v1
	v_mov_b32_e32 v11, v1
	v_mov_b32_e32 v12, v1
	v_mov_b32_e32 v13, v1
	v_mov_b32_e32 v14, v1
	v_mov_b32_e32 v15, v1
	v_mov_b64_e32 v[48:49], v[16:17]
	v_mov_b64_e32 v[64:65], v[16:17]
	v_mov_b64_e32 v[32:33], v[16:17]
	v_mov_b64_e32 v[46:47], v[14:15]
	v_mov_b64_e32 v[44:45], v[12:13]
	v_mov_b64_e32 v[42:43], v[10:11]
	v_mov_b64_e32 v[40:41], v[8:9]
	v_mov_b64_e32 v[38:39], v[6:7]
	v_mov_b64_e32 v[36:37], v[4:5]
	v_mov_b64_e32 v[34:35], v[2:3]
	v_mov_b64_e32 v[62:63], v[14:15]
	v_mov_b64_e32 v[60:61], v[12:13]
	v_mov_b64_e32 v[58:59], v[10:11]
	v_mov_b64_e32 v[56:57], v[8:9]
	v_mov_b64_e32 v[54:55], v[6:7]
	v_mov_b64_e32 v[52:53], v[4:5]
	v_mov_b64_e32 v[50:51], v[2:3]
	v_mov_b64_e32 v[30:31], v[14:15]
	v_mov_b64_e32 v[28:29], v[12:13]
	v_mov_b64_e32 v[26:27], v[10:11]
	v_mov_b64_e32 v[24:25], v[8:9]
	v_mov_b64_e32 v[22:23], v[6:7]
	v_mov_b64_e32 v[20:21], v[4:5]
	v_mov_b64_e32 v[18:19], v[2:3]

.LBB0_1291:
	s_or_b64 exec, exec, s[4:5]
	s_cmp_eq_u64 s[2:3], 0
	s_cbranch_scc1 .Lmoba_skipfill
	v_lshrrev_b32_e32 v236, 6, v200
	v_mul_u32_u24_e32 v236, 0xc00, v236
	v_and_b32_e32 v237, 63, v200
	v_lshl_add_u32 v236, v237, 2, v236
	v_mov_b32_e32 v237, 0
	v_lshl_add_u64 v[236:237], v[236:237], 0, s[50:51]
	v_lshl_add_u64 v[236:237], v[236:237], 0, s[34:35]
	global_load_dword v238, v[236:237], off
	v_add_u32_e32 v206, 0, v200
	v_min_u32_e32 v206, 703, v206
	v_cmp_lt_u32_e32 vcc, 703, v206
	v_mov_b32_e32 v213, 0
	s_nop 0
	v_cndmask_b32_e64 v207, 0, 1, vcc
	v_mul_u32_u24_e32 v208, 704, v207
	v_sub_u32_e32 v208, v206, v208
	v_subrev_u32_e32 v209, 96, v208
	v_max_i32_e32 v210, 0, v209
	v_min_i32_e32 v210, 0x80, v210
	v_lshlrev_b32_e32 v210, 2, v210
	v_add_u32_e32 v210, 0x20004, v210
	ds_read_b32 v210, v210
	v_mul_u32_u24_e32 v211, 0xb00, v207
	v_lshl_add_u32 v211, v208, 2, v211
	v_add_u32_e32 v211, 0x1d000, v211
	v_add_u32_e32 v218, 512, v200
	v_min_u32_e32 v218, 703, v218
	v_cmp_lt_u32_e32 vcc, 703, v218
	v_mov_b32_e32 v225, 0
	s_nop 0
	v_cndmask_b32_e64 v219, 0, 1, vcc
	v_mul_u32_u24_e32 v220, 704, v219
	v_sub_u32_e32 v220, v218, v220
	v_subrev_u32_e32 v221, 96, v220
	v_max_i32_e32 v222, 0, v221
	v_min_i32_e32 v222, 0x80, v222
	v_lshlrev_b32_e32 v222, 2, v222
	v_add_u32_e32 v222, 0x20004, v222
	ds_read_b32 v222, v222
	v_mul_u32_u24_e32 v223, 0xb00, v219
	v_lshl_add_u32 v223, v220, 2, v223
	v_add_u32_e32 v223, 0x1d000, v223
	s_waitcnt lgkmcnt(0)
	v_mul_lo_u32 v210, v210, 12
	v_add3_u32 v212, v210, v207, s94
	v_ashrrev_i32_e32 v213, 31, v212
	v_lshl_add_u64 v[212:213], v[212:213], 2, s[56:57]
	global_load_dword v214, v[212:213], off
	v_mul_lo_u32 v222, v222, 12
	v_add3_u32 v224, v222, v219, s94
	v_ashrrev_i32_e32 v225, 31, v224
	v_lshl_add_u64 v[224:225], v[224:225], 2, s[56:57]
	global_load_dword v226, v[224:225], off
	v_mov_b32_e32 v205, 0xf149f2ca
	v_mov_b32_e32 v204, 0x1ff
	s_waitcnt vmcnt(0)
	v_cmp_gt_u32_e32 vcc, v209, v204
	v_mul_f32_e32 v214, 0x41000000, v214
	s_nop 0
	v_cndmask_b32_e32 v214, v214, v205, vcc
	ds_write_b32 v211, v214
	v_cmp_gt_u32_e32 vcc, v221, v204
	v_mul_f32_e32 v226, 0x41000000, v226
	s_nop 0
	v_cndmask_b32_e32 v226, v226, v205, vcc
	ds_write_b32 v223, v226
	v_lshlrev_b32_e32 v239, 2, v200
	v_add_u32_e32 v239, 0x1e000, v239
	s_waitcnt vmcnt(0)
	ds_write_b32 v239, v238
	s_waitcnt lgkmcnt(0)
	s_barrier
.Lmoba_skipfill:
	v_and_b32_e32 v253, 32, v200
	v_add_u32_e32 v253, 0x1e000, v253
	s_mov_b32 s91, 0x1d094
	s_mov_b32 s32, 0x1d114
	s_xor_b64 s[72:73], s[2:3], -1
	s_and_b64 s[0:1], s[2:3], exec
	s_cselect_b32 s97, s96, s95
	v_ashrrev_i32_e32 v80, 8, v78
	v_lshl_add_u32 v62, s97, 1, v80
	v_and_b32_e32 v81, 0xc0, v78
	v_and_b32_e32 v79, 31, v78
	v_lshl_or_b32 v83, v62, 8, v81
	v_or_b32_e32 v0, v83, v79
	v_ashrrev_i32_e32 v1, 31, v0
	v_lshl_add_u64 v[172:173], s[44:45], 0, v[0:1]
	v_bfe_u32 v82, v78, 5, 1
	v_mad_u64_u32 v[0:1], s[0:1], v172, s84, v[170:171]
	v_mad_i32_i24 v1, v173, s84, v1
	v_lshlrev_b32_e32 v168, 4, v82
	v_lshl_add_u64 v[0:1], v[0:1], 0, v[168:169]
	global_load_dwordx4 v[20:23], v[0:1], off offset:32
	global_load_dwordx4 v[28:31], v[0:1], off
	global_load_dwordx4 v[16:19], v[0:1], off offset:96
	global_load_dwordx4 v[24:27], v[0:1], off offset:64
	v_and_b32_e32 v0, 32, v78
	v_mov_b32_e32 v1, v169
	v_lshl_add_u64 v[12:13], s[34:35], 0, v[0:1]
	v_mov_b32_e32 v63, 0
	v_lshl_add_u64 v[0:1], v[12:13], 0, s[50:51]
	v_cmp_lt_i32_e32 vcc, 0, v62
	v_mov_b32_e32 v64, 0
	s_waitcnt vmcnt(3)
	v_lshlrev_b32_e32 v15, 16, v20
	s_waitcnt vmcnt(2)
	v_lshlrev_b32_e32 v14, 16, v28
	v_and_b32_e32 v45, 0xffff0000, v20
	v_and_b32_e32 v44, 0xffff0000, v28
	v_lshlrev_b32_e32 v43, 16, v21
	v_lshlrev_b32_e32 v42, 16, v29
	v_and_b32_e32 v41, 0xffff0000, v21
	v_and_b32_e32 v40, 0xffff0000, v29
	v_lshlrev_b32_e32 v39, 16, v22
	v_lshlrev_b32_e32 v38, 16, v30
	v_and_b32_e32 v37, 0xffff0000, v22
	v_and_b32_e32 v36, 0xffff0000, v30
	v_lshlrev_b32_e32 v35, 16, v23
	v_lshlrev_b32_e32 v34, 16, v31
	v_and_b32_e32 v33, 0xffff0000, v23
	v_and_b32_e32 v32, 0xffff0000, v31
	s_waitcnt vmcnt(1)
	v_lshlrev_b32_e32 v49, 16, v16
	s_waitcnt vmcnt(0)
	v_lshlrev_b32_e32 v48, 16, v24
	v_and_b32_e32 v61, 0xffff0000, v16
	v_and_b32_e32 v60, 0xffff0000, v24
	v_lshlrev_b32_e32 v59, 16, v17
	v_lshlrev_b32_e32 v58, 16, v25
	v_and_b32_e32 v57, 0xffff0000, v17
	v_and_b32_e32 v56, 0xffff0000, v25
	v_lshlrev_b32_e32 v55, 16, v18
	v_lshlrev_b32_e32 v54, 16, v26
	v_and_b32_e32 v53, 0xffff0000, v18
	v_and_b32_e32 v52, 0xffff0000, v26
	v_lshlrev_b32_e32 v51, 16, v19
	v_lshlrev_b32_e32 v50, 16, v27
	v_and_b32_e32 v47, 0xffff0000, v19
	v_and_b32_e32 v46, 0xffff0000, v27
	s_and_saveexec_b64 s[2:3], vcc
	s_cbranch_execz .LBB0_1293
	ds_read_b128 v[2:5], v253 offset:0
	ds_read_b128 v[6:9], v253 offset:64
	ds_read_b128 v[64:67], v253 offset:16
	ds_read_b128 v[68:71], v253 offset:80
	ds_read_b128 v[72:75], v253 offset:128
	ds_read_b128 v[84:87], v253 offset:192
	ds_read_b128 v[88:91], v253 offset:144
	ds_read_b128 v[92:95], v253 offset:208
	s_waitcnt lgkmcnt(7)
	v_mov_b32_e32 v10, v2
	s_waitcnt lgkmcnt(6)
	v_mov_b32_e32 v11, v6
	v_mov_b32_e32 v6, v3
	v_pk_mul_f32 v[6:7], v[6:7], v[44:45]
	v_mov_b32_e32 v2, v4
	v_mov_b32_e32 v3, v8
	v_mov_b32_e32 v8, v5
	s_waitcnt lgkmcnt(4)
	v_mov_b32_e32 v5, v68
	v_mov_b32_e32 v68, v65
	v_mov_b32_e32 v65, v70
	v_mov_b32_e32 v70, v67
	s_waitcnt lgkmcnt(2)
	v_mov_b32_e32 v67, v84
	v_mov_b32_e32 v84, v73
	v_pk_fma_f32 v[6:7], v[10:11], v[14:15], v[6:7]
	v_mov_b32_e32 v4, v64
	v_mov_b32_e32 v64, v66
	v_mov_b32_e32 v66, v72
	v_pk_mul_f32 v[84:85], v[84:85], v[60:61]
	v_pk_fma_f32 v[2:3], v[2:3], v[42:43], v[6:7]
	v_mov_b32_e32 v72, v74
	v_mov_b32_e32 v73, v86
	v_pk_fma_f32 v[10:11], v[66:67], v[48:49], v[84:85]
	v_pk_fma_f32 v[2:3], v[8:9], v[40:41], v[2:3]
	v_mov_b32_e32 v86, v75
	v_pk_fma_f32 v[6:7], v[72:73], v[58:59], v[10:11]
	v_pk_fma_f32 v[2:3], v[4:5], v[38:39], v[2:3]
	s_waitcnt lgkmcnt(1)
	v_mov_b32_e32 v74, v88
	s_waitcnt lgkmcnt(0)
	v_mov_b32_e32 v75, v92
	v_pk_fma_f32 v[6:7], v[86:87], v[56:57], v[6:7]
	v_pk_fma_f32 v[2:3], v[68:69], v[36:37], v[2:3]
	v_mov_b32_e32 v92, v89
	v_pk_fma_f32 v[4:5], v[74:75], v[54:55], v[6:7]
	v_pk_fma_f32 v[2:3], v[64:65], v[34:35], v[2:3]
	v_mov_b32_e32 v76, v90
	v_mov_b32_e32 v77, v94
	v_pk_fma_f32 v[4:5], v[92:93], v[52:53], v[4:5]
	v_pk_fma_f32 v[2:3], v[70:71], v[32:33], v[2:3]
	v_mov_b32_e32 v94, v91
	v_pk_fma_f32 v[4:5], v[76:77], v[50:51], v[4:5]
	v_add_f32_e32 v2, 0, v2
	v_add_f32_e32 v6, v2, v3
	v_pk_fma_f32 v[2:3], v[94:95], v[46:47], v[4:5]
	s_nop 0
	v_add_f32_e32 v2, v6, v2
	v_add_f32_e32 v64, v2, v3
